# GU epilogue row-scale LDS cache, hit path fully short-circuited (skips the 8 ssq loads, the vmcnt(0) drain and the whole cross-lane reduction; only side-effect instructions + 8 ds_read_b32)
# speedup vs baseline: 1.0149x; 1.0046x over previous
; __device__ __forceinline__ void row_rs8(const float* __restrict__ ssq, int row0, int fq, float (&rs)[2][4]) {
;     f32x4 s4[2][4];
; #pragma unroll
;     for (int ai = 0; ai < 2; ++ai)
; #pragma unroll
;         for (int m = 0; m < 4; ++m) s4[ai][m] = *(const f32x4*)(ssq + (size_t)(row0 + ai * HALF + m * 16) * 16 + 4 * fq);
; #pragma unroll
;     for (int ai = 0; ai < 2; ++ai)
; #pragma unroll
;         for (int m = 0; m < 4; ++m) { float s = (s4[ai][m][0] + s4[ai][m][1]) + (s4[ai][m][2] + s4[ai][m][3]); s += __shfl_xor(s, 16); s += __shfl_xor(s, 32); rs[ai][m] = rsqrtf(s * (1.0f / 1024.0f) + 1e-6f); }
; }
;     __device__ __forceinline__ void operator()(const f32x4 (&acc)[2][2][4][2], const Unit& u, int wr, int wc, int fr, int fq) const {
;         float rs8[2][4]; row_rs8(ssq, u.pm * BM + wr * 64 + fr, fq, rs8);
.LBB0_571:
	s_lshl_b32 s47, s40, 8
	v_add_u32_e32 v180, s47, v186
	s_lshl_b32 s54, s8, 24
	s_or_b32 s54, s54, s47
	s_or_b32 s54, s54, 0x5a
	v_lshrrev_b32_e32 v181, 4, v186
	v_and_b32_e32 v181, 4, v181
	v_add_u32_e32 v181, 0x20400, v181
	ds_read_b32 v179, v181
	s_waitcnt lgkmcnt(0)
	v_readfirstlane_b32 s55, v179
	s_nop 3
	s_cmp_eq_u32 s55, s54
	s_cbranch_scc0 .Lgu_ld
	v_add_u32_e32 v178, 0x80, v180
	v_add_u32_e32 v176, 0x90, v180
	v_add_u32_e32 v174, 0xa0, v180
	v_add_u32_e32 v172, 0xb0, v180
	v_mul_f32_e32 v123, v127, v123
	s_movk_i32 s75, 0x1600
	s_mov_b32 s78, 0x6001000
	v_readlane_b32 s79, v254, 43
	s_mov_b32 s6, 0x2aaaaaab
	v_mov_b32_e32 v182, v126
	v_mov_b32_e32 v154, v94
	v_mov_b32_e32 v152, v78
	v_mov_b32_e32 v146, v62
	v_readlane_b32 s40, v252, 3
	v_readlane_b32 s41, v252, 4
	s_mov_b32 s54, 0x20000
	v_lshl_add_u32 v177, v186, 2, s54
	ds_read_b32 v183, v177
	ds_read_b32 v181, v177 offset:64
	ds_read_b32 v155, v177 offset:128
	ds_read_b32 v153, v177 offset:192
	ds_read_b32 v147, v177 offset:512
	ds_read_b32 v145, v177 offset:576
	ds_read_b32 v139, v177 offset:640
	ds_read_b32 v137, v177 offset:704
	s_waitcnt lgkmcnt(0)
	s_branch .Lgu_rsdone
.Lgu_ld:
	v_ashrrev_i32_e32 v181, 31, v180
	v_lshlrev_b64 v[136:137], 6, v[180:181]
	v_lshl_add_u64 v[136:137], v[166:167], 0, v[136:137]
	global_load_dwordx4 v[182:185], v[136:137], off
	v_or_b32_e32 v136, 16, v180
	v_ashrrev_i32_e32 v137, 31, v136
	v_lshlrev_b64 v[136:137], 6, v[136:137]
	v_lshl_add_u64 v[136:137], v[166:167], 0, v[136:137]
	global_load_dwordx4 v[192:195], v[136:137], off
	v_or_b32_e32 v136, 32, v180
	v_ashrrev_i32_e32 v137, 31, v136
	v_lshlrev_b64 v[136:137], 6, v[136:137]
	v_lshl_add_u64 v[136:137], v[166:167], 0, v[136:137]
	global_load_dwordx4 v[156:159], v[136:137], off
	v_or_b32_e32 v136, 48, v180
	v_ashrrev_i32_e32 v137, 31, v136
	v_lshlrev_b64 v[136:137], 6, v[136:137]
	v_lshl_add_u64 v[136:137], v[166:167], 0, v[136:137]
	global_load_dwordx4 v[152:155], v[136:137], off
	v_add_u32_e32 v178, 0x80, v180
	v_ashrrev_i32_e32 v179, 31, v178
	v_lshlrev_b64 v[136:137], 6, v[178:179]
	v_add_u32_e32 v176, 0x90, v180
	v_lshl_add_u64 v[136:137], v[166:167], 0, v[136:137]
	v_ashrrev_i32_e32 v177, 31, v176
	global_load_dwordx4 v[148:151], v[136:137], off
	v_lshlrev_b64 v[136:137], 6, v[176:177]
	v_lshl_add_u64 v[136:137], v[166:167], 0, v[136:137]
	global_load_dwordx4 v[144:147], v[136:137], off
	v_add_u32_e32 v174, 0xa0, v180
	v_ashrrev_i32_e32 v175, 31, v174
	v_lshlrev_b64 v[136:137], 6, v[174:175]
	v_add_u32_e32 v172, 0xb0, v180
	v_lshl_add_u64 v[136:137], v[166:167], 0, v[136:137]
	v_ashrrev_i32_e32 v173, 31, v172
	global_load_dwordx4 v[140:143], v[136:137], off
	v_lshlrev_b64 v[136:137], 6, v[172:173]
	v_lshl_add_u64 v[136:137], v[166:167], 0, v[136:137]
	global_load_dwordx4 v[136:139], v[136:137], off
	v_and_b32_e32 v175, 64, v234
	v_xor_b32_e32 v173, 16, v234
	v_add_u32_e32 v177, 64, v175
	v_cmp_lt_i32_e32 vcc, v173, v177
	s_mov_b32 s40, 0x358637bd
	s_mov_b32 s54, 0x3a800000
	v_cndmask_b32_e32 v173, v234, v173, vcc
	v_lshlrev_b32_e32 v175, 2, v173
	v_xor_b32_e32 v173, 32, v234
	v_cmp_lt_i32_e32 vcc, v173, v177
	v_mul_f32_e32 v123, v127, v123
	s_movk_i32 s75, 0x1600
	v_cndmask_b32_e32 v173, v234, v173, vcc
	v_lshlrev_b32_e32 v173, 2, v173
	s_mov_b32 s78, 0x6001000
	v_readlane_b32 s79, v254, 43
	s_mov_b32 s6, 0x2aaaaaab
	s_waitcnt vmcnt(0)
	v_mov_b32_e32 v196, v183
	v_mov_b32_e32 v197, v184
	v_mov_b32_e32 v183, v185
	v_pk_add_f32 v[182:183], v[196:197], v[182:183]
	v_mov_b32_e32 v184, v193
	v_mov_b32_e32 v185, v194
	v_mov_b32_e32 v193, v195
	v_pk_add_f32 v[184:185], v[184:185], v[192:193]
	v_mov_b32_e32 v193, v182
	v_mov_b32_e32 v192, v184
	v_mov_b32_e32 v182, v185
	v_pk_add_f32 v[182:183], v[192:193], v[182:183]
	ds_bpermute_b32 v185, v175, v183
	ds_bpermute_b32 v184, v175, v182
	v_mov_b32_e32 v192, v157
	v_mov_b32_e32 v193, v158
	v_mov_b32_e32 v157, v159
	v_mov_b32_e32 v158, v153
	v_mov_b32_e32 v159, v154
	v_mov_b32_e32 v153, v155
	v_pk_add_f32 v[156:157], v[192:193], v[156:157]
	v_pk_add_f32 v[152:153], v[158:159], v[152:153]
	s_waitcnt lgkmcnt(0)
	v_pk_add_f32 v[182:183], v[182:183], v[184:185]
	v_mov_b32_e32 v154, v152
	v_mov_b32_e32 v155, v156
	v_mov_b32_e32 v156, v153
	ds_bpermute_b32 v185, v173, v183
	ds_bpermute_b32 v184, v173, v182
	v_pk_add_f32 v[152:153], v[154:155], v[156:157]
	ds_bpermute_b32 v155, v175, v153
	ds_bpermute_b32 v154, v175, v152
	v_mov_b32_e32 v156, v149
	v_mov_b32_e32 v157, v150
	v_mov_b32_e32 v149, v151
	v_mov_b32_e32 v150, v145
	v_mov_b32_e32 v151, v146
	v_mov_b32_e32 v145, v147
	s_waitcnt lgkmcnt(2)
; __device__ __forceinline__ void row_rs8(const float* __restrict__ ssq, int row0, int fq, float (&rs)[2][4]) {
;     f32x4 s4[2][4];
; #pragma unroll
;     for (int ai = 0; ai < 2; ++ai)
; #pragma unroll
;         for (int m = 0; m < 4; ++m) s4[ai][m] = *(const f32x4*)(ssq + (size_t)(row0 + ai * HALF + m * 16) * 16 + 4 * fq);
; #pragma unroll
;     for (int ai = 0; ai < 2; ++ai)
; #pragma unroll
;         for (int m = 0; m < 4; ++m) { float s = (s4[ai][m][0] + s4[ai][m][1]) + (s4[ai][m][2] + s4[ai][m][3]); s += __shfl_xor(s, 16); s += __shfl_xor(s, 32); rs[ai][m] = rsqrtf(s * (1.0f / 1024.0f) + 1e-6f); }
; }
	v_pk_add_f32 v[182:183], v[182:183], v[184:185]
	v_mov_b64_e32 v[184:185], s[40:41]
	v_pk_add_f32 v[148:149], v[156:157], v[148:149]
	v_pk_add_f32 v[144:145], v[150:151], v[144:145]
	v_pk_fma_f32 v[182:183], v[182:183], s[54:55], v[184:185] op_sel_hi:[1,0,0]
	s_waitcnt lgkmcnt(0)
	v_pk_add_f32 v[152:153], v[152:153], v[154:155]
	v_mov_b32_e32 v146, v144
	v_mov_b32_e32 v147, v148
	v_mov_b32_e32 v148, v145
	v_mul_f32_e32 v177, 0x4b800000, v183
	v_cmp_gt_f32_e64 s[40:41], s22, v183
	ds_bpermute_b32 v155, v173, v153
	ds_bpermute_b32 v154, v173, v152
	v_pk_add_f32 v[144:145], v[146:147], v[148:149]
	v_cndmask_b32_e64 v177, v183, v177, s[40:41]
	ds_bpermute_b32 v147, v175, v145
	ds_bpermute_b32 v146, v175, v144
	v_rsq_f32_e32 v177, v177
	v_mov_b32_e32 v148, v141
	v_mov_b32_e32 v149, v142
	v_mov_b32_e32 v141, v143
	v_mov_b32_e32 v142, v137
	v_mov_b32_e32 v143, v138
	v_mov_b32_e32 v137, v139
	s_waitcnt lgkmcnt(2)
	v_pk_add_f32 v[152:153], v[152:153], v[154:155]
	v_pk_add_f32 v[140:141], v[148:149], v[140:141]
	v_pk_add_f32 v[136:137], v[142:143], v[136:137]
	v_mul_f32_e32 v179, 0x45800000, v177
	v_pk_fma_f32 v[152:153], v[152:153], s[54:55], v[184:185] op_sel_hi:[1,0,0]
	s_waitcnt lgkmcnt(0)
	v_pk_add_f32 v[144:145], v[144:145], v[146:147]
	v_mov_b32_e32 v138, v136
	v_mov_b32_e32 v139, v140
	v_mov_b32_e32 v140, v137
	v_cmp_gt_f32_e32 vcc, s22, v182
	v_cndmask_b32_e64 v183, v177, v179, s[40:41]
	v_mul_f32_e32 v177, 0x4b800000, v182
	v_mul_f32_e32 v154, 0x4b800000, v153
	v_cmp_gt_f32_e64 s[40:41], s22, v153
	ds_bpermute_b32 v147, v173, v145
	ds_bpermute_b32 v146, v173, v144
	v_pk_add_f32 v[136:137], v[138:139], v[140:141]
	v_cndmask_b32_e32 v177, v182, v177, vcc
	v_cndmask_b32_e64 v153, v153, v154, s[40:41]
	ds_bpermute_b32 v139, v175, v137
	ds_bpermute_b32 v138, v175, v136
	v_rsq_f32_e32 v177, v177
	v_rsq_f32_e32 v153, v153
	s_waitcnt lgkmcnt(2)
	v_pk_add_f32 v[144:145], v[144:145], v[146:147]
	v_mov_b32_e32 v182, v126
	v_mul_f32_e32 v179, 0x45800000, v177
	v_mul_f32_e32 v154, 0x45800000, v153
	v_pk_fma_f32 v[144:145], v[144:145], s[54:55], v[184:185] op_sel_hi:[1,0,0]
	s_waitcnt lgkmcnt(0)
	v_pk_add_f32 v[136:137], v[136:137], v[138:139]
	v_cndmask_b32_e32 v181, v177, v179, vcc
	v_cmp_gt_f32_e32 vcc, s22, v152
	v_cndmask_b32_e64 v155, v153, v154, s[40:41]
	v_mul_f32_e32 v153, 0x4b800000, v152
	v_mul_f32_e32 v146, 0x4b800000, v145
	v_cmp_gt_f32_e64 s[40:41], s22, v145
	ds_bpermute_b32 v139, v173, v137
	ds_bpermute_b32 v138, v173, v136
	v_cndmask_b32_e32 v152, v152, v153, vcc
	v_cndmask_b32_e64 v145, v145, v146, s[40:41]
	v_rsq_f32_e32 v152, v152
	v_rsq_f32_e32 v145, v145
	s_waitcnt lgkmcnt(0)
	v_pk_add_f32 v[136:137], v[136:137], v[138:139]
	v_mov_b32_e32 v154, v94
	v_mul_f32_e32 v153, 0x45800000, v152
	v_mul_f32_e32 v146, 0x45800000, v145
	v_pk_fma_f32 v[136:137], v[136:137], s[54:55], v[184:185] op_sel_hi:[1,0,0]
	v_cndmask_b32_e32 v153, v152, v153, vcc
	v_cmp_gt_f32_e32 vcc, s22, v144
	v_cndmask_b32_e64 v147, v145, v146, s[40:41]
	v_mul_f32_e32 v145, 0x4b800000, v144
	v_mul_f32_e32 v138, 0x4b800000, v137
	v_cmp_gt_f32_e64 s[40:41], s22, v137
	v_cndmask_b32_e32 v144, v144, v145, vcc
	v_rsq_f32_e32 v144, v144
	v_cndmask_b32_e64 v137, v137, v138, s[40:41]
	v_rsq_f32_e32 v137, v137
	v_mov_b32_e32 v152, v78
	v_mul_f32_e32 v145, 0x45800000, v144
	v_cndmask_b32_e32 v145, v144, v145, vcc
	v_mul_f32_e32 v138, 0x45800000, v137
	v_cmp_gt_f32_e32 vcc, s22, v136
	v_cndmask_b32_e64 v139, v137, v138, s[40:41]
	v_mul_f32_e32 v137, 0x4b800000, v136
	v_cndmask_b32_e32 v136, v136, v137, vcc
	v_rsq_f32_e32 v136, v136
	v_readlane_b32 s40, v252, 3
	v_readlane_b32 s41, v252, 4
	v_mov_b32_e32 v146, v62
	v_mul_f32_e32 v137, 0x45800000, v136
	v_cndmask_b32_e32 v137, v136, v137, vcc
	s_mov_b32 s54, 0x20000
	v_lshl_add_u32 v177, v186, 2, s54
	ds_write_b32 v177, v183
	ds_write_b32 v177, v181 offset:64
	ds_write_b32 v177, v155 offset:128
	ds_write_b32 v177, v153 offset:192
	ds_write_b32 v177, v147 offset:512
	ds_write_b32 v177, v145 offset:576
	ds_write_b32 v177, v139 offset:640
	ds_write_b32 v177, v137 offset:704
	s_lshl_b32 s54, s8, 24
	s_or_b32 s54, s54, s47
	s_or_b32 s54, s54, 0x5a
	v_lshrrev_b32_e32 v179, 4, v186
	v_and_b32_e32 v179, 4, v179
	v_add_u32_e32 v179, 0x20400, v179
	v_mov_b32_e32 v175, s54
	s_waitcnt lgkmcnt(0)
	ds_write_b32 v179, v175
